# retention tile loop: uniform-mask ballot (v_cndmask+v_cmp_ne) replaced by s_not_b64, diag-tile test as one scalar branch with the diagonal pack out of line, tile-end count via s_cmp_lg_u64+s_addc inst
# speedup vs baseline: 1.0053x; 1.0053x over previous
; __device__ __forceinline__ void p2_ret(const Frame& F, ArgsP a, int layer) {
;     ...
;             for (int kt = 0; kt < ntile; ++kt) {
;                 const bool cv = cvhi < CV_HALF_ITEMS && ((cvtile++ & 1) == 0); f32x4 cvv[8], cvsc[2];
;                 if (cv) { const CvU cu = cv_decode(a, F.ws, cvhi, layer); cv_load(cu, lane, cvv, cvsc); }
;                 const int bf = kt & 1; const bool pre = kt + 1 < ntile;
.LBB0_357:
	s_waitcnt lgkmcnt(0)
	s_barrier
	s_cmp_lg_u64 s[2:3], 0
	s_addc_u32 s37, s37, 0
	s_sub_i32 s97, s97, 64
	s_addk_i32 s30, 0x80
	s_add_i32 s31, s31, 0x8000
	s_add_i32 s27, s27, 0x40000
	s_add_i32 s91, s91, 1
	s_cmp_eq_u32 s11, s30
	s_cbranch_scc1 .LBB0_410
.LBB0_358:
	s_cmp_lt_i32 s36, s93
	s_cselect_b64 s[2:3], -1, 0
	s_bitcmp0_b32 s37, 0
	s_cselect_b64 s[4:5], -1, 0
	s_and_b64 s[4:5], s[2:3], s[4:5]
	s_not_b64 s[38:39], s[4:5]
	s_andn2_b64 vcc, exec, s[4:5]
	s_cbranch_vccnz .LBB0_383
	s_ashr_i32 s15, s36, 1
	s_cmpk_gt_i32 s15, 0x3ff
	s_cselect_b64 s[6:7], -1, 0
	s_cmpk_lt_i32 s15, 0x400
	s_mov_b64 s[70:71], 0
	s_cbranch_scc1 .LBB0_365
	s_mov_b64 s[4:5], -1
	s_cmpk_gt_u32 s15, 0x13ff
	s_mov_b64 s[12:13], -1
	s_cbranch_scc0 .LBB0_362
	s_add_i32 s14, s15, 0xffffec00
	s_mov_b64 s[12:13], 0

; #define LAS __attribute__((address_space(3)))
; __device__ __forceinline__ void p2_ret(const Frame& F, ArgsP a, int layer) {
;     ...
;                 { const LAS unsigned char* kb = lds + RT_K0 + bf * 32768 + (32 * wc + kap) * 512;
;     ...
;                   bf16x8 ka[2], kd[2], kc[2];
;                   RT_KRD(ka, 0); RT_KRD(kd, 2); __builtin_amdgcn_sched_barrier(0);
;                   RT_KRD(kc, 4); RT_KMM(ka, 0); if (pre) { RT_DMA_K(kt + 1, bf ^ 1, 0); RT_DMA_V(kt + 1, bf ^ 1, 0); } __builtin_amdgcn_sched_barrier(0);
;                   RT_KRD(ka, 6); RT_KMM(kd, 2); __builtin_amdgcn_sched_barrier(0);
;                   RT_KRD(kd, 8); RT_KMM(kc, 4); if (pre) { RT_DMA_K(kt + 1, bf ^ 1, 1); RT_DMA_V(kt + 1, bf ^ 1, 1); } __builtin_amdgcn_sched_barrier(0);
;                   RT_KRD(kc, 10); RT_KMM(ka, 6); __builtin_amdgcn_sched_barrier(0);
;                   RT_KRD(ka, 12); RT_KMM(kd, 8); if (pre) { RT_DMA_K(kt + 1, bf ^ 1, 2); RT_DMA_V(kt + 1, bf ^ 1, 2); } __builtin_amdgcn_sched_barrier(0);
;                   RT_KRD(kd, 14); RT_KMM(kc, 10); __builtin_amdgcn_sched_barrier(0);
;                   RT_KMM(ka, 12); if (pre) { RT_DMA_K(kt + 1, bf ^ 1, 3); RT_DMA_V(kt + 1, bf ^ 1, 3); } __builtin_amdgcn_sched_barrier(0);
;                   RT_KMM(kd, 14); __builtin_amdgcn_sched_barrier(0);
;     ...
;                 }
;                 { const bool diag = kt >= 2 * qi;
;                   unsigned pk[8];
;                   if (!diag) { const float tf = __builtin_amdgcn_exp2f((float)(128 * (qi - (kt >> 1))) * lg2);
; #pragma unroll
;                       for (int i = 0; i < 8; ++i) pk[i] = cvt_pk_bf16(st[2 * i] * tf, st[2 * i + 1] * tf);
;                   } else { const int lim = wr * 32 + l31 + (2 * qi - kt) * 64 - 32 * wc - 8 * hh;
; #pragma unroll
;                       for (int i = 0; i < 8; ++i) { const int r0 = 2 * i, r1 = 2 * i + 1, o0 = 16 * (r0 >> 3) + (r0 & 7), o1 = 16 * (r1 >> 3) + (r1 & 7);
;                           pk[i] = cvt_pk_bf16((o0 <= lim) ? st[r0] : 0.f, (o1 <= lim) ? st[r1] : 0.f); } }
;                   LAS unsigned char* pw = lds + RT_P + ((wr * 2 + wc) * 2) * 1024 + lane * 16;
;                   *(LAS u32x4*)pw = (u32x4){pk[0], pk[1], pk[2], pk[3]}; *(LAS u32x4*)(pw + 1024) = (u32x4){pk[4], pk[5], pk[6], pk[7]}; }
.LBB0_383:
	v_mov_b32_e32 v0, v207
	s_and_b32 s6, s31, 0x8000
	v_lshlrev_b32_e32 v99, 1, v0
	v_lshrrev_b32_e32 v100, 1, v0
	v_and_b32_e32 v98, 19, v0
	v_and_b32_e32 v99, 8, v99
	v_and_b32_e32 v100, 4, v100
	v_or3_b32 v115, v99, v98, v100
	v_ashrrev_i32_e32 v116, 5, v0
	s_add_i32 s4, s6, 0
	v_or_b32_e32 v98, s80, v115
	v_lshl_add_u32 v227, v98, 9, s4
	v_bitop3_b32 v228, v115, v116, 15 bitop3:0x6c
	v_or_b32_e32 v229, 2, v116
	v_bitop3_b32 v229, v115, v229, 15 bitop3:0x6c
	v_lshl_add_u32 v228, v228, 4, v227
	v_lshl_add_u32 v229, v229, 4, v227
	ds_read_b128 v[98:101], v228
	ds_read_b128 v[190:193], v229
	v_or_b32_e32 v230, 4, v116
	v_bitop3_b32 v230, v115, v230, 15 bitop3:0x6c
	v_or_b32_e32 v231, 6, v116
	v_lshl_add_u32 v230, v230, 4, v227
	v_bitop3_b32 v231, v115, v231, 15 bitop3:0x6c
	v_lshl_add_u32 v231, v231, 4, v227
	ds_read_b128 v[194:197], v230
	ds_read_b128 v[198:201], v231
	v_and_b32_e32 v117, 31, v0
	v_or_b32_e32 v250, 8, v116
	s_xor_b32 s4, s6, 0x8000
	v_bitop3_b32 v250, v115, v250, 15 bitop3:0x6c
	v_or_b32_e32 v251, 10, v116
	s_add_i32 s5, s22, s4
	v_lshl_add_u32 v250, v250, 4, v227
	v_bitop3_b32 v251, v115, v251, 15 bitop3:0x6c
	v_lshl_add_u32 v251, v251, 4, v227
	ds_read_b128 v[202:205], v250
	ds_read_b128 v[212:215], v251
	s_add_i32 s7, s25, s30
	s_add_i32 m0, s33, s4
	s_add_i32 s12, s7, 0x80
	s_mov_b32 s46, s42
	s_mov_b32 s47, s43
	buffer_load_dwordx4 v225, s[44:47], s12 offen lds
	s_waitcnt lgkmcnt(5)
	v_mfma_f32_32x32x16_bf16 v[98:113], v[98:101], v[118:121], 0
	s_waitcnt lgkmcnt(4)
	v_mfma_f32_32x32x16_bf16 v[98:113], v[190:193], v[122:125], v[98:113]
	v_or_b32_e32 v252, 12, v116
	v_or_b32_e32 v253, 14, v116
	v_bitop3_b32 v252, v115, v252, 15 bitop3:0x6c
	v_bitop3_b32 v253, v115, v253, 15 bitop3:0x6c
	v_lshl_add_u32 v252, v252, 4, v227
	v_lshl_add_u32 v253, v253, 4, v227
	ds_read_b128 v[190:193], v252
	ds_read_b128 v[216:219], v253
	s_waitcnt lgkmcnt(5)
	v_mfma_f32_32x32x16_bf16 v[98:113], v[194:197], v[126:129], v[98:113]
	s_add_i32 s4, s4, 0
	s_waitcnt lgkmcnt(4)
	v_mfma_f32_32x32x16_bf16 v[98:113], v[198:201], v[130:133], v[98:113]
	s_add_i32 s12, s27, 0xfffe0000
	s_add_i32 s4, s4, 0x10000
	ds_read_b128 v[194:197], v228 offset:256
	ds_read_b128 v[198:201], v229 offset:256
	s_add_i32 m0, s4, s24
	s_add_i32 s12, s7, 0x100080
	buffer_load_dwordx4 v225, s[44:47], s12 offen lds
	s_waitcnt lgkmcnt(5)
	v_mfma_f32_32x32x16_bf16 v[98:113], v[202:205], v[134:137], v[98:113]
	s_waitcnt lgkmcnt(4)
	v_mfma_f32_32x32x16_bf16 v[98:113], v[212:215], v[138:141], v[98:113]
	ds_read_b128 v[202:205], v230 offset:256
	ds_read_b128 v[212:215], v231 offset:256
	s_waitcnt lgkmcnt(5)
	v_mfma_f32_32x32x16_bf16 v[98:113], v[190:193], v[142:145], v[98:113]
	s_add_i32 s12, s27, 0xffff0000
	s_waitcnt lgkmcnt(4)
	v_mfma_f32_32x32x16_bf16 v[98:113], v[216:219], v[146:149], v[98:113]
	ds_read_b128 v[190:193], v250 offset:256
	ds_read_b128 v[216:219], v251 offset:256
	s_add_i32 m0, s4, s26
	s_add_i32 s12, s7, 0x200080
	buffer_load_dwordx4 v225, s[44:47], s12 offen lds
	s_waitcnt lgkmcnt(5)
	v_mfma_f32_32x32x16_bf16 v[98:113], v[194:197], v[150:153], v[98:113]
	s_waitcnt lgkmcnt(4)
	v_mfma_f32_32x32x16_bf16 v[98:113], v[198:201], v[154:157], v[98:113]
	s_waitcnt lgkmcnt(3)
	v_mfma_f32_32x32x16_bf16 v[98:113], v[202:205], v[158:161], v[98:113]
	ds_read_b128 v[194:197], v252 offset:256
	ds_read_b128 v[198:201], v253 offset:256
	s_waitcnt lgkmcnt(4)
	v_mfma_f32_32x32x16_bf16 v[98:113], v[212:215], v[162:165], v[98:113]
	s_add_i32 s7, s7, 0x300080
	s_add_i32 m0, s4, s28
	s_waitcnt lgkmcnt(3)
	v_mfma_f32_32x32x16_bf16 v[98:113], v[190:193], v[166:169], v[98:113]
	buffer_load_dwordx4 v225, s[44:47], s7 offen lds
	s_waitcnt lgkmcnt(2)
	v_mfma_f32_32x32x16_bf16 v[98:113], v[216:219], v[170:173], v[98:113]
	s_waitcnt lgkmcnt(1)
	v_mfma_f32_32x32x16_bf16 v[98:113], v[194:197], v[174:177], v[98:113]
	s_waitcnt lgkmcnt(0)
	v_mfma_f32_32x32x16_bf16 v[98:113], v[198:201], v[178:181], v[98:113]
	v_lshlrev_b32_e32 v250, 3, v115
	v_and_b32_e32 v250, 0x70, v250
	s_add_i32 s13, s64, s6
	v_lshl_add_u32 v251, v115, 7, s13
	v_lshlrev_b32_e32 v252, 4, v116
	s_lshl_b32 s14, s80, 1
	v_xad_u32 v246, v250, v252, v251
	v_add_u32_e32 v253, 32, v252
	v_xad_u32 v247, v250, v253, v251
	v_xor_b32_e32 v246, s14, v246
	v_xor_b32_e32 v247, s14, v247
	v_xor_b32_e32 v248, 64, v246
	v_xor_b32_e32 v249, 64, v247
	ds_read_b128 v[234:237], v246
	ds_read_b128 v[238:241], v247
	s_cmp_ge_u32 s91, s29
	s_cbranch_scc1 .Ldiag_pack
	v_cvt_pk_bf16_f32 v190, v98, v99
	v_cvt_pk_bf16_f32 v191, v100, v101
	v_cvt_pk_bf16_f32 v192, v102, v103
	v_cvt_pk_bf16_f32 v193, v104, v105
	v_cvt_pk_bf16_f32 v194, v106, v107
	v_cvt_pk_bf16_f32 v195, v108, v109
	v_cvt_pk_bf16_f32 v196, v110, v111
	v_cvt_pk_bf16_f32 v197, v112, v113

; __device__ __forceinline__ unsigned cvt_pk_bf16(float lo, float hi) { unsigned r; asm volatile("v_cvt_pk_bf16_f32 %0, %1, %2" : "=v"(r) : "v"(lo), "v"(hi)); return r; }
; __device__ __forceinline__ void p2_ret(const Frame& F, ArgsP a, int layer) {
;     ...
;                   } else { const int lim = wr * 32 + l31 + (2 * qi - kt) * 64 - 32 * wc - 8 * hh;
; #pragma unroll
;                       for (int i = 0; i < 8; ++i) { const int r0 = 2 * i, r1 = 2 * i + 1, o0 = 16 * (r0 >> 3) + (r0 & 7), o1 = 16 * (r1 >> 3) + (r1 & 7);
;                           pk[i] = cvt_pk_bf16((o0 <= lim) ? st[r0] : 0.f, (o1 <= lim) ? st[r1] : 0.f); } }
.Ldiag_pack:
	v_lshlrev_b32_e32 v190, 3, v116
	v_sub_u32_e32 v117, v117, v190
	v_add_u32_e32 v117, s97, v117
	v_cmp_lt_i32_e32 vcc, -1, v117
	s_nop 3
	v_cndmask_b32_e32 v190, 0, v98, vcc
	v_cmp_lt_i32_e32 vcc, 0, v117
	s_nop 1
	v_cndmask_b32_e32 v191, 0, v99, vcc
	v_cmp_lt_i32_e32 vcc, 1, v117
	v_cvt_pk_bf16_f32 v190, v190, v191
	s_nop 1
	v_cndmask_b32_e32 v191, 0, v100, vcc
	v_cmp_lt_i32_e32 vcc, 2, v117
	s_nop 1
	v_cndmask_b32_e32 v192, 0, v101, vcc
	v_cmp_lt_i32_e32 vcc, 3, v117
	v_cvt_pk_bf16_f32 v191, v191, v192
	s_nop 1
	v_cndmask_b32_e32 v192, 0, v102, vcc
	v_cmp_lt_i32_e32 vcc, 4, v117
	s_nop 1
	v_cndmask_b32_e32 v193, 0, v103, vcc
	v_cmp_lt_i32_e32 vcc, 5, v117
	v_cvt_pk_bf16_f32 v192, v192, v193
	s_nop 1
	v_cndmask_b32_e32 v193, 0, v104, vcc
	v_cmp_lt_i32_e32 vcc, 6, v117
	s_nop 1
	v_cndmask_b32_e32 v194, 0, v105, vcc
	v_cmp_lt_i32_e32 vcc, 15, v117
	v_cvt_pk_bf16_f32 v193, v193, v194
	s_nop 1
	v_cndmask_b32_e32 v194, 0, v106, vcc
	v_cmp_lt_i32_e32 vcc, 16, v117
	s_nop 1
	v_cndmask_b32_e32 v195, 0, v107, vcc
	v_cmp_lt_i32_e32 vcc, 17, v117
	v_cvt_pk_bf16_f32 v194, v194, v195
	s_nop 1
	v_cndmask_b32_e32 v195, 0, v108, vcc
	v_cmp_lt_i32_e32 vcc, 18, v117
	s_nop 1
	v_cndmask_b32_e32 v196, 0, v109, vcc
	v_cmp_lt_i32_e32 vcc, 19, v117
	v_cvt_pk_bf16_f32 v195, v195, v196
	s_nop 1
	v_cndmask_b32_e32 v196, 0, v110, vcc
	v_cmp_lt_i32_e32 vcc, 20, v117
	s_nop 1
	v_cndmask_b32_e32 v197, 0, v111, vcc
	v_cmp_lt_i32_e32 vcc, 21, v117
	v_cvt_pk_bf16_f32 v196, v196, v197
	s_nop 1
	v_cndmask_b32_e32 v197, 0, v112, vcc
	v_cmp_lt_i32_e32 vcc, 22, v117
	s_nop 1
	v_cndmask_b32_e32 v117, 0, v113, vcc
	v_cvt_pk_bf16_f32 v197, v197, v117
	s_branch .LBB0_387
